# DSA: per-item mask rows staged once into LDS by LDS-DMA (8 pieces per item) instead of one gather load per wave per tile
# speedup vs baseline: 1.0342x; 1.0050x over previous
; template <int DQK, int W1, int DV, int VW, int MODE> ...
;     ...
;     if (MODE == 1) { mwn[0] = maskrow[(kb >> 5)]; mwn[1] = maskrow[(kb >> 5) + 1]; }
;   };
;   stage_tile(kbase0, 0);
;   asm volatile("s_waitcnt vmcnt(0)" ::: "memory");
;   __syncthreads();
;   for (int t = 0; t < ntiles; ++t) {
;     const int kb = kbase0 + t * 64;
;     const unsigned bufa = lds0 + (unsigned)((t & 1) * BUF);
;     const unsigned mw0 = mwn[0], mw1 = mwn[1];
;     if (t + 1 < ntiles) stage_tile(kb + 64, (t + 1) & 1);
.Ldsa_p1_done:
	v_lshlrev_b32_e32 v210, 2, v82
	s_lshl_b32 s100, s29, 5
	v_add_u32_e32 v210, s100, v210
	v_mov_b32_e32 v211, v1
	v_lshl_add_u64 v[210:211], v[96:97], 0, v[210:211]
	s_add_i32 m0, s18, 0xd000
	v_and_b32_e32 v208, 31, v179
	global_load_lds_dwordx4 v[210:211], off
	v_lshlrev_b32_e32 v208, 4, v208
	v_add_u32_e32 v208, 0xd000, v208
	s_waitcnt vmcnt(0)
	v_or3_b32 v99, v0, v2, s0
	v_mov_b32_e32 v0, v1
	v_mov_b32_e32 v2, v1
	v_mov_b32_e32 v3, v1
	v_mov_b32_e32 v4, v1
	v_mov_b32_e32 v5, v1
	v_mov_b32_e32 v6, v1
	v_mov_b32_e32 v7, v1
	v_mov_b32_e32 v8, v1
	v_mov_b32_e32 v9, v1
	v_mov_b32_e32 v10, v1
	v_mov_b32_e32 v11, v1
	v_mov_b32_e32 v12, v1
	v_mov_b32_e32 v13, v1
	v_mov_b64_e32 v[32:33], v[14:15]
	v_mov_b64_e32 v[30:31], v[12:13]
	v_mov_b64_e32 v[28:29], v[10:11]
	v_mov_b64_e32 v[26:27], v[8:9]
	v_mov_b64_e32 v[24:25], v[6:7]
	v_mov_b64_e32 v[22:23], v[4:5]
	v_mov_b64_e32 v[20:21], v[2:3]
	v_mov_b64_e32 v[18:19], v[0:1]
	v_mov_b64_e32 v[16:17], v[14:15]
	s_add_i32 s73, s18, 0
	s_add_i32 s86, s28, 0x7a1
	s_waitcnt lgkmcnt(0)
	v_mov_b32_e32 v89, v88
	s_add_i32 s87, s69, 1
	v_sub_u32_e32 v118, v247, v82
	s_mov_b32 s0, 0
	v_mov_b32_e32 v119, 0
	v_mov_b32_e32 v98, 0xefa18f08
	s_mov_b32 s94, 64
	v_mov_b64_e32 v[14:15], v[12:13]
	v_mov_b64_e32 v[12:13], v[10:11]
	v_mov_b64_e32 v[10:11], v[8:9]
	v_mov_b64_e32 v[8:9], v[6:7]
	v_mov_b64_e32 v[6:7], v[4:5]
	v_mov_b64_e32 v[4:5], v[2:3]
	v_mov_b64_e32 v[2:3], v[0:1]
	s_mov_b64 s[28:29], 0xf4000
	s_mov_b32 s100, 0
	s_mov_b32 s101, 0x8800
	s_waitcnt vmcnt(0)
	s_barrier
	s_add_i32 s95, s0, 1
	s_cmp_ge_u32 s0, s69
	s_cbranch_scc1 .LBB0_1333
.LBB0_1328:
	s_lshr_b32 s54, s95, 1
	s_lshl_b32 s54, s54, 9
	s_bitcmp1_b32 s95, 0
	s_cselect_b32 s1, 8, 0
	s_add_i32 s54, s54, s1
	v_add_u32_e32 v34, s54, v208
	ds_read_b64 v[100:101], v34
	s_cmp_ge_u32 s95, s69
	s_cbranch_scc1 .LBB0_1334
	s_mov_b32 s1, s101
	s_andn2_b64 vcc, exec, s[12:13]
	s_cbranch_vccz .LBB0_1346
	s_andn2_b64 vcc, exec, s[14:15]
	s_cbranch_vccz .LBB0_1347
